# neighbourhood attention: rpb bias lookups batched (unconditional ds_read + fmac + cndmask) instead of 40 exec-masked serialized LDS round trips per key tile
# speedup vs baseline: 1.0189x; 1.0091x over previous
; #define MFMA32(a, b, c) __builtin_amdgcn_mfma_f32_32x32x16_bf16((a), (b), (c), 0, 0, 0)
; DI int crow(int i, int h) { return (i & 3) + 8 * (i >> 2) + 4 * h; }
; template <int DK, int DV, int MODE, int QB, bool PACK = false>
; DI void attn_item(const AttArgs& a, int q0, int t_lo, int t_hi) {
;     ...
;     if constexpr (MODE == 2) active = (tile >= r0) && (tile < r0 + 8);
;     if constexpr (MODE == 1) active = (tile * 64 + 63 >= wq0 - 128) && (tile * 64 <= wq0 + 32 * QB - 1 + 128);
;     if (active) {
;       f32x16 s[QB][2];
; #pragma unroll
;       for (int qb = 0; qb < QB; ++qb)
; #pragma unroll
;         for (int kb = 0; kb < 2; ++kb) {
; #pragma unroll
;           for (int i = 0; i < 16; ++i) s[qb][kb][i] = 0.f;
;           const unsigned char* kp = Kb + (kb * 32 + r) * KST + h * 16;
; #pragma unroll
;           for (int st = 0; st < NKS; ++st) {
;             const bf16x8 kf = *(const bf16x8*)(kp + st * 32);
;             s[qb][kb] = MFMA32(kf, qf[qb][st], s[qb][kb]);
;           }
;         }
; #pragma unroll
;       for (int qb = 0; qb < QB; ++qb) {
;         const int qidx = wq0 + qb * 32 + r;
;         float mloc = -1e30f;
; #pragma unroll
;         for (int kb = 0; kb < 2; ++kb)
; #pragma unroll
;           for (int i = 0; i < 16; ++i) {
;             float tt = s[qb][kb][i];
;             if constexpr (MODE == 1) {
;               const int kidx = tile * 64 + kb * 32 + crow(i, h);
;               const int d = kidx - qidx;
;               tt = (d <= 128 && d >= -128) ? tt : -1e30f;
;               s[qb][kb][i] = tt;
;             }
;             if constexpr (MODE == 2) {
;               const int kc = kb * 32 + crow(i, h);
;               const bool ok = (kc >= c0[qb]) && (kc < c0[qb] + 16);
;               const int bi = ok ? ((tile - rq + 7) * 31 + kc - cq[qb] + 15) : 0;
;               tt = ok ? fmaf(tt, scale, rpbs[bi]) : -1e30f;
;               s[qb][kb][i] = tt;
;             }
;             mloc = fmaxf(mloc, tt);
.LBB0_661:
	v_cmp_ge_u32_e64 s[8:9], s33, v179
	v_cmp_lt_u32_e32 vcc, s33, v180
	s_and_b64 vcc, s[8:9], vcc
	s_and_saveexec_b64 s[8:9], vcc
	s_cbranch_execz .LBB0_747
	s_mul_i32 s33, s46, 0x4800
	v_add3_u32 v0, s33, v176, v182
	ds_read_b128 v[4:7], v0
	ds_read_b128 v[8:11], v0 offset:32
	ds_read_b128 v[12:15], v0 offset:64
	ds_read_b128 v[80:83], v0 offset:96
	ds_read_b128 v[188:191], v0 offset:4608
	ds_read_b128 v[192:195], v0 offset:4640
	ds_read_b128 v[196:199], v0 offset:4672
	ds_read_b128 v[200:203], v0 offset:4704
	s_waitcnt lgkmcnt(7)
	v_mfma_f32_32x32x16_bf16 v[84:99], v[4:7], v[148:151], 0
	v_readlane_b32 s12, v254, 60
	v_mov_b32_e32 v1, 0xf149f2ca
	v_mov_b32_e32 v0, 0xf149f2ca
	v_readlane_b32 s13, v254, 61
	v_mfma_f32_32x32x16_bf16 v[116:131], v[4:7], v[132:135], 0
	s_waitcnt lgkmcnt(6)
	v_mfma_f32_32x32x16_bf16 v[84:99], v[8:11], v[152:155], v[84:99]
	v_mfma_f32_32x32x16_bf16 v[116:131], v[8:11], v[136:139], v[116:131]
	s_waitcnt lgkmcnt(5)
	v_mfma_f32_32x32x16_bf16 v[84:99], v[12:15], v[156:159], v[84:99]
	v_mfma_f32_32x32x16_bf16 v[116:131], v[12:15], v[140:143], v[116:131]
	s_waitcnt lgkmcnt(4)
	v_mfma_f32_32x32x16_bf16 v[84:99], v[80:83], v[160:163], v[84:99]
	v_mfma_f32_32x32x16_bf16 v[116:131], v[80:83], v[144:147], v[116:131]
	s_waitcnt lgkmcnt(3)
	v_mfma_f32_32x32x16_bf16 v[100:115], v[188:191], v[132:135], 0
	v_mfma_f32_32x32x16_bf16 v[80:95], v[188:191], v[148:151], 0
	s_waitcnt lgkmcnt(2)
	v_mfma_f32_32x32x16_bf16 v[100:115], v[192:195], v[136:139], v[100:115]
	v_mfma_f32_32x32x16_bf16 v[80:95], v[192:195], v[152:155], v[80:95]
	s_waitcnt lgkmcnt(1)
	v_mfma_f32_32x32x16_bf16 v[100:115], v[196:199], v[140:143], v[100:115]
	v_mfma_f32_32x32x16_bf16 v[80:95], v[196:199], v[156:159], v[80:95]
	s_waitcnt lgkmcnt(0)
	v_mfma_f32_32x32x16_bf16 v[100:115], v[200:203], v[144:147], v[100:115]
	v_mfma_f32_32x32x16_bf16 v[80:95], v[200:203], v[160:163], v[80:95]
	ds_read_b32 v0, v185 offset:32
	ds_read_b32 v1, v185 offset:36
	ds_read_b32 v4, v185 offset:40
	ds_read_b32 v5, v185 offset:44
	ds_read_b32 v6, v185 offset:64
	ds_read_b32 v7, v185 offset:68
	ds_read_b32 v8, v185 offset:72
	ds_read_b32 v9, v185 offset:76
	ds_read_b32 v10, v185 offset:96
	ds_read_b32 v11, v185 offset:100
	ds_read_b32 v12, v185 offset:104
	ds_read_b32 v13, v185 offset:108
	ds_read_b32 v14, v185 offset:128
	ds_read_b32 v15, v185 offset:132
	ds_read_b32 v104, v185 offset:136
	ds_read_b32 v105, v185 offset:140
	ds_read_b32 v106, v185 offset:160
	ds_read_b32 v107, v185 offset:164
	s_waitcnt lgkmcnt(0)
	v_fmac_f32_e32 v0, 0x3e000000, v116
	v_cndmask_b32_e64 v0, v235, v0, s[12:13]
	v_readlane_b32 s12, v254, 62
	v_readlane_b32 s13, v254, 63
	v_fmac_f32_e32 v1, 0x3e000000, v117
	s_nop 0
	v_cndmask_b32_e64 v1, v235, v1, s[12:13]
	v_readlane_b32 s12, v255, 0
	v_readlane_b32 s13, v255, 1
	v_fmac_f32_e32 v4, 0x3e000000, v118
	s_nop 0
	v_cndmask_b32_e64 v4, v235, v4, s[12:13]
	v_readlane_b32 s12, v255, 2
	v_readlane_b32 s13, v255, 3
	v_fmac_f32_e32 v5, 0x3e000000, v119
	s_nop 0
	v_cndmask_b32_e64 v5, v235, v5, s[12:13]
	v_readlane_b32 s12, v255, 4
	v_readlane_b32 s13, v255, 5
	v_fmac_f32_e32 v6, 0x3e000000, v120
	s_nop 0
	v_cndmask_b32_e64 v6, v235, v6, s[12:13]
	v_readlane_b32 s12, v255, 6
	v_readlane_b32 s13, v255, 7
	v_fmac_f32_e32 v7, 0x3e000000, v121
	s_nop 0
	v_cndmask_b32_e64 v7, v235, v7, s[12:13]
	v_readlane_b32 s12, v255, 8
	v_readlane_b32 s13, v255, 9
	v_fmac_f32_e32 v8, 0x3e000000, v122
	s_nop 0
	v_cndmask_b32_e64 v8, v235, v8, s[12:13]
	v_readlane_b32 s12, v255, 10
	v_readlane_b32 s13, v255, 11
	v_fmac_f32_e32 v9, 0x3e000000, v123
	s_nop 0
	v_cndmask_b32_e64 v9, v235, v9, s[12:13]
	v_readlane_b32 s12, v255, 12
	v_readlane_b32 s13, v255, 13
	v_fmac_f32_e32 v10, 0x3e000000, v124
	s_nop 0
	v_cndmask_b32_e64 v10, v235, v10, s[12:13]
	v_fmac_f32_e32 v11, 0x3e000000, v125
	v_cndmask_b32_e64 v11, v235, v11, s[24:25]
	v_fmac_f32_e32 v12, 0x3e000000, v126
	v_cndmask_b32_e64 v12, v235, v12, s[52:53]
	v_fmac_f32_e32 v13, 0x3e000000, v127
	v_cndmask_b32_e64 v13, v235, v13, s[20:21]
	v_fmac_f32_e32 v14, 0x3e000000, v128
	v_cndmask_b32_e64 v14, v235, v14, s[54:55]
	v_fmac_f32_e32 v15, 0x3e000000, v129
	v_cndmask_b32_e64 v15, v235, v15, s[56:57]
	v_fmac_f32_e32 v104, 0x3e000000, v130
	v_cndmask_b32_e64 v104, v235, v104, s[58:59]
	v_fmac_f32_e32 v105, 0x3e000000, v131
	v_cndmask_b32_e64 v105, v235, v105, s[60:61]
	v_fmac_f32_e32 v106, 0x3e000000, v100
	v_cndmask_b32_e64 v106, v235, v106, s[62:63]
	v_fmac_f32_e32 v107, 0x3e000000, v101
	v_cndmask_b32_e64 v107, v235, v107, s[64:65]
	ds_read_b32 v100, v185 offset:168
	ds_read_b32 v101, v185 offset:172
	s_waitcnt lgkmcnt(0)
	v_fmac_f32_e32 v100, 0x3e000000, v102
	v_cndmask_b32_e64 v100, v235, v100, s[66:67]
	v_fmac_f32_e32 v101, 0x3e000000, v103
	v_cndmask_b32_e64 v101, v235, v101, s[68:69]
; DI int crow(int i, int h) { return (i & 3) + 8 * (i >> 2) + 4 * h; }
; DI float fexp2(float x) { return __builtin_amdgcn_exp2f(x); }
; template <int DK, int DV, int MODE, int QB, bool PACK = false>
; DI void attn_item(const AttArgs& a, int q0, int t_lo, int t_hi) {
;     ...
; #pragma unroll
;       for (int qb = 0; qb < QB; ++qb) {
;         const int qidx = wq0 + qb * 32 + r;
;         float mloc = -1e30f;
; #pragma unroll
;         for (int kb = 0; kb < 2; ++kb)
; #pragma unroll
;           for (int i = 0; i < 16; ++i) {
;             float tt = s[qb][kb][i];
;             if constexpr (MODE == 1) {
;               const int kidx = tile * 64 + kb * 32 + crow(i, h);
;               const int d = kidx - qidx;
;               tt = (d <= 128 && d >= -128) ? tt : -1e30f;
;               s[qb][kb][i] = tt;
;             }
;             if constexpr (MODE == 2) {
;               const int kc = kb * 32 + crow(i, h);
;               const bool ok = (kc >= c0[qb]) && (kc < c0[qb] + 16);
;               const int bi = ok ? ((tile - rq + 7) * 31 + kc - cq[qb] + 15) : 0;
;               tt = ok ? fmaf(tt, scale, rpbs[bi]) : -1e30f;
;               s[qb][kb][i] = tt;
;             }
;             mloc = fmaxf(mloc, tt);
;           }
;         mloc = fmaxf(mloc, __shfl_xor(mloc, 32));
;         if (__any((mloc - m[qb]) * cexp > 8.f)) {
;           const float mnew = fmaxf(m[qb], mloc);
;           const float alpha = fexp2((m[qb] - mnew) * cexp);
;           m[qb] = mnew;
;           lsum[qb] *= alpha;
; #pragma unroll
;           for (int d = 0; d < NDB; ++d)
; #pragma unroll
;             for (int i = 0; i < 16; ++i) o[qb][d][i] *= alpha;
;         }
.LBB0_702:
	v_max_f32_e32 v3, v0, v0
	v_max_f32_e32 v3, 0xf149f2ca, v3
	v_max3_f32 v3, v3, v1, v4
	v_max3_f32 v3, v3, v5, v6
	v_max3_f32 v3, v3, v7, v8
	v_max3_f32 v3, v3, v9, v10
	v_max3_f32 v3, v3, v11, v12
	v_max3_f32 v3, v3, v13, v14
	v_max3_f32 v3, v3, v15, v104
	v_max3_f32 v3, v3, v105, v106
	v_and_b32_e32 v103, 64, v225
	v_max3_f32 v102, v3, v107, v100
	v_xor_b32_e32 v3, 32, v225
	v_add_u32_e32 v103, 64, v103
	v_cmp_lt_i32_e32 vcc, v3, v103
	s_mov_b32 s46, 0xf149f2ca
	v_max3_f32 v102, v102, v101, s46
	v_cndmask_b32_e32 v3, v225, v3, vcc
	v_lshlrev_b32_e32 v3, 2, v3
	ds_bpermute_b32 v103, v3, v102
	s_mov_b32 s46, 0x41000000
	s_waitcnt lgkmcnt(0)
	v_max_f32_e32 v103, v103, v103
	v_max_f32_e32 v102, v102, v103
	v_sub_f32_e32 v103, v102, v187
	v_mul_f32_e32 v103, 0x3fb8aa3b, v103
	v_cmp_lt_f32_e32 vcc, s46, v103
	s_cbranch_vccz .LBB0_704
	v_max_f32_e32 v102, v102, v102
	v_max_f32_e32 v103, v187, v187
	v_max_f32_e32 v103, v103, v102
	v_sub_f32_e32 v102, v187, v103
	v_mul_f32_e32 v102, 0x3fb8aa3b, v102
	v_exp_f32_e32 v102, v102
	v_mov_b32_e32 v187, v103
	v_mul_f32_e32 v183, v183, v102
	v_pk_mul_f32 v[78:79], v[78:79], v[102:103] op_sel_hi:[1,0]
	v_pk_mul_f32 v[76:77], v[76:77], v[102:103] op_sel_hi:[1,0]
	v_pk_mul_f32 v[74:75], v[74:75], v[102:103] op_sel_hi:[1,0]
	v_pk_mul_f32 v[72:73], v[72:73], v[102:103] op_sel_hi:[1,0]
	v_pk_mul_f32 v[70:71], v[70:71], v[102:103] op_sel_hi:[1,0]
	v_pk_mul_f32 v[68:69], v[68:69], v[102:103] op_sel_hi:[1,0]
	v_pk_mul_f32 v[66:67], v[66:67], v[102:103] op_sel_hi:[1,0]
	v_pk_mul_f32 v[64:65], v[64:65], v[102:103] op_sel_hi:[1,0]
	v_pk_mul_f32 v[62:63], v[62:63], v[102:103] op_sel_hi:[1,0]
	v_pk_mul_f32 v[60:61], v[60:61], v[102:103] op_sel_hi:[1,0]
	v_pk_mul_f32 v[58:59], v[58:59], v[102:103] op_sel_hi:[1,0]
	v_pk_mul_f32 v[56:57], v[56:57], v[102:103] op_sel_hi:[1,0]
	v_pk_mul_f32 v[54:55], v[54:55], v[102:103] op_sel_hi:[1,0]
	v_pk_mul_f32 v[52:53], v[52:53], v[102:103] op_sel_hi:[1,0]
	v_pk_mul_f32 v[50:51], v[50:51], v[102:103] op_sel_hi:[1,0]
	v_pk_mul_f32 v[48:49], v[48:49], v[102:103] op_sel_hi:[1,0]
.LBB0_704:
	ds_read_b32 v102, v185
	ds_read_b32 v103, v185 offset:4
	ds_read_b32 v110, v185 offset:40
	ds_read_b32 v111, v185 offset:44
	ds_read_b32 v112, v185 offset:64
	ds_read_b32 v113, v185 offset:68
	ds_read_b32 v114, v185 offset:72
	ds_read_b32 v115, v185 offset:76
	ds_read_b32 v120, v185 offset:96
	ds_read_b32 v121, v185 offset:100
	ds_read_b32 v122, v185 offset:104
	ds_read_b32 v123, v185 offset:108
	s_waitcnt lgkmcnt(0)
	v_fmac_f32_e32 v102, 0x3e000000, v96
	v_cndmask_b32_e64 v102, v235, v102, s[70:71]
	v_fmac_f32_e32 v103, 0x3e000000, v97
	v_cndmask_b32_e64 v103, v235, v103, s[72:73]
	v_fmac_f32_e32 v110, 0x3e000000, v82
	v_cndmask_b32_e64 v110, v235, v110, s[82:83]
	v_fmac_f32_e32 v111, 0x3e000000, v83
	v_cndmask_b32_e64 v111, v235, v111, s[84:85]
	v_fmac_f32_e32 v112, 0x3e000000, v84
	v_cndmask_b32_e64 v112, v235, v112, s[38:39]
	v_fmac_f32_e32 v113, 0x3e000000, v85
	v_cndmask_b32_e64 v113, v235, v113, s[0:1]
	v_fmac_f32_e32 v114, 0x3e000000, v86
	v_cndmask_b32_e64 v114, v235, v114, s[40:41]
	v_fmac_f32_e32 v115, 0x3e000000, v87
	v_cndmask_b32_e64 v115, v235, v115, s[42:43]
	v_fmac_f32_e32 v120, 0x3e000000, v88
	v_cndmask_b32_e64 v120, v235, v120, s[86:87]
	v_fmac_f32_e32 v121, 0x3e000000, v89
	v_cndmask_b32_e64 v121, v235, v121, s[88:89]
	v_fmac_f32_e32 v122, 0x3e000000, v90
	v_cndmask_b32_e64 v122, v235, v122, s[90:91]
	v_fmac_f32_e32 v123, 0x3e000000, v91
	v_cndmask_b32_e64 v123, v235, v123, s[92:93]
	ds_read_b32 v96, v185 offset:8
	ds_read_b32 v97, v185 offset:12
	ds_read_b32 v90, v185 offset:128
	ds_read_b32 v91, v185 offset:132
	s_waitcnt lgkmcnt(0)
	v_fmac_f32_e32 v96, 0x3e000000, v98
	v_cndmask_b32_e64 v96, v235, v96, s[74:75]
	v_fmac_f32_e32 v97, 0x3e000000, v99
	v_cndmask_b32_e64 v97, v235, v97, s[76:77]
	v_fmac_f32_e32 v90, 0x3e000000, v92
	v_cndmask_b32_e64 v90, v235, v90, s[94:95]
	v_fmac_f32_e32 v91, 0x3e000000, v93
	v_cndmask_b32_e64 v91, v235, v91, s[96:97]
	ds_read_b32 v98, v185 offset:32
	ds_read_b32 v99, v185 offset:36
	ds_read_b32 v92, v185 offset:136
	ds_read_b32 v93, v185 offset:140
	s_waitcnt lgkmcnt(0)
	v_fmac_f32_e32 v98, 0x3e000000, v80
	v_cndmask_b32_e64 v98, v235, v98, s[78:79]
	v_fmac_f32_e32 v99, 0x3e000000, v81
	v_cndmask_b32_e64 v99, v235, v99, s[80:81]
	v_fmac_f32_e32 v92, 0x3e000000, v94
	v_cndmask_b32_e64 v92, v235, v92, s[4:5]
	v_fmac_f32_e32 v93, 0x3e000000, v95
	v_cndmask_b32_e64 v93, v235, v93, s[6:7]
.LBB0_744:
	s_mov_b32 s46, 0xf149f2ca
	v_max3_f32 v80, v102, s46, v103
	v_max3_f32 v80, v80, v96, v97
	v_max3_f32 v80, v80, v98, v99
	v_max3_f32 v80, v80, v110, v111
	v_max3_f32 v80, v80, v112, v113
	v_max3_f32 v80, v80, v114, v115
	v_max3_f32 v80, v80, v120, v121
	v_max3_f32 v80, v80, v122, v123
	v_max3_f32 v80, v80, v90, v91
	v_max3_f32 v80, v80, v92, v93
	ds_bpermute_b32 v3, v3, v80
	s_mov_b32 s46, 0x41000000
	s_waitcnt lgkmcnt(0)
	v_max_f32_e32 v3, v3, v3
	v_max_f32_e32 v3, v80, v3
	v_sub_f32_e32 v80, v3, v186
	v_mul_f32_e32 v80, 0x3fb8aa3b, v80
	v_cmp_lt_f32_e32 vcc, s46, v80
	s_cbranch_vccz .LBB0_746
	v_max_f32_e32 v3, v3, v3
	v_max_f32_e32 v80, v186, v186
	v_max_f32_e32 v3, v80, v3
	v_sub_f32_e32 v80, v186, v3
	v_mul_f32_e32 v80, 0x3fb8aa3b, v80
	v_exp_f32_e32 v80, v80
	v_mov_b32_e32 v186, v3
	v_mul_f32_e32 v177, v177, v80
	v_pk_mul_f32 v[46:47], v[46:47], v[80:81] op_sel_hi:[1,0]
	v_pk_mul_f32 v[44:45], v[44:45], v[80:81] op_sel_hi:[1,0]
	v_pk_mul_f32 v[42:43], v[42:43], v[80:81] op_sel_hi:[1,0]
	v_pk_mul_f32 v[40:41], v[40:41], v[80:81] op_sel_hi:[1,0]
	v_pk_mul_f32 v[38:39], v[38:39], v[80:81] op_sel_hi:[1,0]
	v_pk_mul_f32 v[36:37], v[36:37], v[80:81] op_sel_hi:[1,0]
	v_pk_mul_f32 v[34:35], v[34:35], v[80:81] op_sel_hi:[1,0]
	v_pk_mul_f32 v[32:33], v[32:33], v[80:81] op_sel_hi:[1,0]
	v_pk_mul_f32 v[30:31], v[30:31], v[80:81] op_sel_hi:[1,0]
	v_pk_mul_f32 v[28:29], v[28:29], v[80:81] op_sel_hi:[1,0]
	v_pk_mul_f32 v[26:27], v[26:27], v[80:81] op_sel_hi:[1,0]
	v_pk_mul_f32 v[24:25], v[24:25], v[80:81] op_sel_hi:[1,0]
	v_pk_mul_f32 v[22:23], v[22:23], v[80:81] op_sel_hi:[1,0]
	v_pk_mul_f32 v[20:21], v[20:21], v[80:81] op_sel_hi:[1,0]
	v_pk_mul_f32 v[18:19], v[18:19], v[80:81] op_sel_hi:[1,0]
	v_pk_mul_f32 v[16:17], v[16:17], v[80:81] op_sel_hi:[1,0]
